# P0 adaLN GEMV: silu staging loads issued together, weight loads pipelined 32-56 deep via SGPR base
# baseline (speedup 1.0000x reference)
; __device__ __forceinline__ void p0_prologue(const Args& A, LAS unsigned char* lds) {
;     ...
;         for (int e = tid; e < 4096; e += 512) { const float v = A.c[e]; sc[e] = v / (1.0f + __expf(-v)); }
;         __syncthreads();
.LBB0_16:
	s_and_saveexec_b64 s[8:9], s[0:1]
	s_cbranch_execz .LBB0_19
	v_mov_b64_e32 v[8:9], v[4:5]
	global_load_dword v40, v[8:9], off
	v_lshl_add_u64 v[8:9], v[8:9], 0, s[6:7]
	global_load_dword v41, v[8:9], off
	v_lshl_add_u64 v[8:9], v[8:9], 0, s[6:7]
	global_load_dword v42, v[8:9], off
	v_lshl_add_u64 v[8:9], v[8:9], 0, s[6:7]
	global_load_dword v43, v[8:9], off
	v_lshl_add_u64 v[8:9], v[8:9], 0, s[6:7]
	global_load_dword v44, v[8:9], off
	v_lshl_add_u64 v[8:9], v[8:9], 0, s[6:7]
	global_load_dword v45, v[8:9], off
	v_lshl_add_u64 v[8:9], v[8:9], 0, s[6:7]
	global_load_dword v46, v[8:9], off
	v_lshl_add_u64 v[8:9], v[8:9], 0, s[6:7]
	global_load_dword v47, v[8:9], off
	s_waitcnt vmcnt(7)
	v_mul_f32_e32 v13, 0xbfb8aa3b, v40
	v_exp_f32_e32 v13, v13
	s_nop 0
	v_add_f32_e32 v13, 1.0, v13
	v_div_scale_f32 v14, s[24:25], v13, v13, v40
	v_rcp_f32_e32 v15, v14
	v_div_scale_f32 v23, vcc, v40, v13, v40
	v_fma_f32 v24, -v14, v15, 1.0
	v_fmac_f32_e32 v15, v24, v15
	v_mul_f32_e32 v24, v23, v15
	v_fma_f32 v25, -v14, v24, v23
	v_fmac_f32_e32 v24, v25, v15
	v_fma_f32 v14, -v14, v24, v23
	v_div_fmas_f32 v14, v14, v15, v24
	v_div_fixup_f32 v12, v14, v13, v40
	ds_write_b32 v21, v12
	s_waitcnt vmcnt(6)
	v_mul_f32_e32 v13, 0xbfb8aa3b, v41
	v_exp_f32_e32 v13, v13
	s_nop 0
	v_add_f32_e32 v13, 1.0, v13
	v_div_scale_f32 v14, s[24:25], v13, v13, v41
	v_rcp_f32_e32 v15, v14
	v_div_scale_f32 v23, vcc, v41, v13, v41
	v_fma_f32 v24, -v14, v15, 1.0
	v_fmac_f32_e32 v15, v24, v15
	v_mul_f32_e32 v24, v23, v15
	v_fma_f32 v25, -v14, v24, v23
	v_fmac_f32_e32 v24, v25, v15
	v_fma_f32 v14, -v14, v24, v23
	v_div_fmas_f32 v14, v14, v15, v24
	v_div_fixup_f32 v12, v14, v13, v41
	ds_write_b32 v21, v12 offset:2048
	s_waitcnt vmcnt(5)
	v_mul_f32_e32 v13, 0xbfb8aa3b, v42
	v_exp_f32_e32 v13, v13
	s_nop 0
	v_add_f32_e32 v13, 1.0, v13
	v_div_scale_f32 v14, s[24:25], v13, v13, v42
	v_rcp_f32_e32 v15, v14
	v_div_scale_f32 v23, vcc, v42, v13, v42
	v_fma_f32 v24, -v14, v15, 1.0
	v_fmac_f32_e32 v15, v24, v15
	v_mul_f32_e32 v24, v23, v15
	v_fma_f32 v25, -v14, v24, v23
	v_fmac_f32_e32 v24, v25, v15
	v_fma_f32 v14, -v14, v24, v23
	v_div_fmas_f32 v14, v14, v15, v24
	v_div_fixup_f32 v12, v14, v13, v42
	ds_write_b32 v21, v12 offset:4096
	s_waitcnt vmcnt(4)
	v_mul_f32_e32 v13, 0xbfb8aa3b, v43
	v_exp_f32_e32 v13, v13
	s_nop 0
	v_add_f32_e32 v13, 1.0, v13
	v_div_scale_f32 v14, s[24:25], v13, v13, v43
	v_rcp_f32_e32 v15, v14
	v_div_scale_f32 v23, vcc, v43, v13, v43
	v_fma_f32 v24, -v14, v15, 1.0
	v_fmac_f32_e32 v15, v24, v15
	v_mul_f32_e32 v24, v23, v15
	v_fma_f32 v25, -v14, v24, v23
	v_fmac_f32_e32 v24, v25, v15
	v_fma_f32 v14, -v14, v24, v23
	v_div_fmas_f32 v14, v14, v15, v24
	v_div_fixup_f32 v12, v14, v13, v43
	ds_write_b32 v21, v12 offset:6144
	s_waitcnt vmcnt(3)
	v_mul_f32_e32 v13, 0xbfb8aa3b, v44
	v_exp_f32_e32 v13, v13
	s_nop 0
	v_add_f32_e32 v13, 1.0, v13
	v_div_scale_f32 v14, s[24:25], v13, v13, v44
	v_rcp_f32_e32 v15, v14
	v_div_scale_f32 v23, vcc, v44, v13, v44
	v_fma_f32 v24, -v14, v15, 1.0
	v_fmac_f32_e32 v15, v24, v15
	v_mul_f32_e32 v24, v23, v15
	v_fma_f32 v25, -v14, v24, v23
	v_fmac_f32_e32 v24, v25, v15
	v_fma_f32 v14, -v14, v24, v23
	v_div_fmas_f32 v14, v14, v15, v24
	v_div_fixup_f32 v12, v14, v13, v44
	ds_write_b32 v21, v12 offset:8192
	s_waitcnt vmcnt(2)
	v_mul_f32_e32 v13, 0xbfb8aa3b, v45
	v_exp_f32_e32 v13, v13
	s_nop 0
	v_add_f32_e32 v13, 1.0, v13
	v_div_scale_f32 v14, s[24:25], v13, v13, v45
	v_rcp_f32_e32 v15, v14
	v_div_scale_f32 v23, vcc, v45, v13, v45
	v_fma_f32 v24, -v14, v15, 1.0
	v_fmac_f32_e32 v15, v24, v15
	v_mul_f32_e32 v24, v23, v15
	v_fma_f32 v25, -v14, v24, v23
	v_fmac_f32_e32 v24, v25, v15
	v_fma_f32 v14, -v14, v24, v23
	v_div_fmas_f32 v14, v14, v15, v24
	v_div_fixup_f32 v12, v14, v13, v45
	ds_write_b32 v21, v12 offset:10240
	s_waitcnt vmcnt(1)
	v_mul_f32_e32 v13, 0xbfb8aa3b, v46
	v_exp_f32_e32 v13, v13
	s_nop 0
	v_add_f32_e32 v13, 1.0, v13
	v_div_scale_f32 v14, s[24:25], v13, v13, v46
	v_rcp_f32_e32 v15, v14
	v_div_scale_f32 v23, vcc, v46, v13, v46
	v_fma_f32 v24, -v14, v15, 1.0
	v_fmac_f32_e32 v15, v24, v15
	v_mul_f32_e32 v24, v23, v15
	v_fma_f32 v25, -v14, v24, v23
	v_fmac_f32_e32 v24, v25, v15
	v_fma_f32 v14, -v14, v24, v23
	v_div_fmas_f32 v14, v14, v15, v24
	v_div_fixup_f32 v12, v14, v13, v46
	ds_write_b32 v21, v12 offset:12288
	s_waitcnt vmcnt(0)
	v_mul_f32_e32 v13, 0xbfb8aa3b, v47
	v_exp_f32_e32 v13, v13
	s_nop 0
	v_add_f32_e32 v13, 1.0, v13
	v_div_scale_f32 v14, s[24:25], v13, v13, v47
	v_rcp_f32_e32 v15, v14
	v_div_scale_f32 v23, vcc, v47, v13, v47
	v_fma_f32 v24, -v14, v15, 1.0
	v_fmac_f32_e32 v15, v24, v15
	v_mul_f32_e32 v24, v23, v15
	v_fma_f32 v25, -v14, v24, v23
	v_fmac_f32_e32 v24, v25, v15
	v_fma_f32 v14, -v14, v24, v23
	v_div_fmas_f32 v14, v14, v15, v24
	v_div_fixup_f32 v12, v14, v13, v47
	ds_write_b32 v21, v12 offset:14336
; __device__ __forceinline__ void p0_prologue(const Args& A, LAS unsigned char* lds) {
;     ...
;         const int l = it / 48, col = (it % 48) * 64 + (tid & 63), kc = tid >> 6;
;         const float* w = A.w_ada + (size_t)l * 1024 * 3072 + col;
;         float a0 = 0.f, a1 = 0.f, a2 = 0.f, a3 = 0.f;
; #pragma unroll 8
;         for (int k = kc * 128; k < kc * 128 + 128; ++k) { const float wv = w[(size_t)k * 3072]; a0 += sc[k] * wv; a1 += sc[1024 + k] * wv; a2 += sc[2048 + k] * wv; a3 += sc[3072 + k] * wv; }
;         red[(kc * 4 + 0) * 64 + (tid & 63)] = a0; red[(kc * 4 + 1) * 64 + (tid & 63)] = a1; red[(kc * 4 + 2) * 64 + (tid & 63)] = a2; red[(kc * 4 + 3) * 64 + (tid & 63)] = a3;
.LBB0_19:
	s_or_b64 exec, exec, s[8:9]
	s_mul_hi_i32 s8, s22, 0x2aaaaaab
	s_lshr_b32 s9, s8, 31
	s_ashr_i32 s12, s8, 3
	s_add_i32 s12, s12, s9
	s_mul_i32 s8, s12, 48
	s_sub_i32 s8, s22, s8
	v_lshl_or_b32 v8, s8, 6, v16
	v_ashrrev_i32_e32 v9, 31, v8
	v_lshlrev_b64 v[10:11], 2, v[8:9]
	v_mad_i64_i32 v[10:11], s[8:9], s12, v22, v[10:11]
	v_mov_b32_e32 v12, 0
	v_lshl_add_u64 v[10:11], v[6:7], 0, v[10:11]
	s_mov_b64 s[8:9], 0
	v_mov_b32_e32 v9, v3
	v_mov_b32_e32 v13, v12
	v_mov_b32_e32 v14, v12
	v_mov_b32_e32 v15, v12
	s_waitcnt lgkmcnt(0)
	s_barrier
	v_readfirstlane_b32 s8, v10
	v_readfirstlane_b32 s9, v11
	v_and_b32_e32 v88, 63, v2
	v_lshlrev_b32_e32 v88, 2, v88
	s_nop 3
	global_load_dword v100, v88, s[8:9]
	s_add_u32 s8, s8, 0x3000
	s_addc_u32 s9, s9, 0
	global_load_dword v101, v88, s[8:9]
	s_add_u32 s8, s8, 0x3000
	s_addc_u32 s9, s9, 0
	global_load_dword v102, v88, s[8:9]
	s_add_u32 s8, s8, 0x3000
	s_addc_u32 s9, s9, 0
	global_load_dword v103, v88, s[8:9]
	s_add_u32 s8, s8, 0x3000
	s_addc_u32 s9, s9, 0
	global_load_dword v104, v88, s[8:9]
	s_add_u32 s8, s8, 0x3000
	s_addc_u32 s9, s9, 0
	global_load_dword v105, v88, s[8:9]
	s_add_u32 s8, s8, 0x3000
	s_addc_u32 s9, s9, 0
	global_load_dword v106, v88, s[8:9]
	s_add_u32 s8, s8, 0x3000
	s_addc_u32 s9, s9, 0
	global_load_dword v107, v88, s[8:9]
	s_add_u32 s8, s8, 0x3000
	s_addc_u32 s9, s9, 0
	global_load_dword v108, v88, s[8:9]
	s_add_u32 s8, s8, 0x3000
	s_addc_u32 s9, s9, 0
	global_load_dword v109, v88, s[8:9]
	s_add_u32 s8, s8, 0x3000
	s_addc_u32 s9, s9, 0
	global_load_dword v110, v88, s[8:9]
	s_add_u32 s8, s8, 0x3000
	s_addc_u32 s9, s9, 0
	global_load_dword v111, v88, s[8:9]
	s_add_u32 s8, s8, 0x3000
	s_addc_u32 s9, s9, 0
	global_load_dword v112, v88, s[8:9]
	s_add_u32 s8, s8, 0x3000
	s_addc_u32 s9, s9, 0
	global_load_dword v113, v88, s[8:9]
	s_add_u32 s8, s8, 0x3000
	s_addc_u32 s9, s9, 0
	global_load_dword v114, v88, s[8:9]
	s_add_u32 s8, s8, 0x3000
	s_addc_u32 s9, s9, 0
	global_load_dword v115, v88, s[8:9]
	s_add_u32 s8, s8, 0x3000
	s_addc_u32 s9, s9, 0
	global_load_dword v116, v88, s[8:9]
	s_add_u32 s8, s8, 0x3000
	s_addc_u32 s9, s9, 0
	global_load_dword v117, v88, s[8:9]
	s_add_u32 s8, s8, 0x3000
	s_addc_u32 s9, s9, 0
	global_load_dword v118, v88, s[8:9]
	s_add_u32 s8, s8, 0x3000
	s_addc_u32 s9, s9, 0
	global_load_dword v119, v88, s[8:9]
	s_add_u32 s8, s8, 0x3000
	s_addc_u32 s9, s9, 0
	global_load_dword v120, v88, s[8:9]
	s_add_u32 s8, s8, 0x3000
	s_addc_u32 s9, s9, 0
	global_load_dword v121, v88, s[8:9]
	s_add_u32 s8, s8, 0x3000
	s_addc_u32 s9, s9, 0
	global_load_dword v122, v88, s[8:9]
	s_add_u32 s8, s8, 0x3000
	s_addc_u32 s9, s9, 0
	global_load_dword v123, v88, s[8:9]
	s_add_u32 s8, s8, 0x3000
	s_addc_u32 s9, s9, 0
	global_load_dword v124, v88, s[8:9]
	s_add_u32 s8, s8, 0x3000
	s_addc_u32 s9, s9, 0
	global_load_dword v125, v88, s[8:9]
	s_add_u32 s8, s8, 0x3000
	s_addc_u32 s9, s9, 0
	global_load_dword v126, v88, s[8:9]
	s_add_u32 s8, s8, 0x3000
	s_addc_u32 s9, s9, 0
	global_load_dword v127, v88, s[8:9]
	s_add_u32 s8, s8, 0x3000
	s_addc_u32 s9, s9, 0
	global_load_dword v128, v88, s[8:9]
	s_add_u32 s8, s8, 0x3000
	s_addc_u32 s9, s9, 0
	global_load_dword v129, v88, s[8:9]
	s_add_u32 s8, s8, 0x3000
	s_addc_u32 s9, s9, 0
	global_load_dword v130, v88, s[8:9]
	s_add_u32 s8, s8, 0x3000
	s_addc_u32 s9, s9, 0
	global_load_dword v131, v88, s[8:9]
	s_add_u32 s8, s8, 0x3000
	s_addc_u32 s9, s9, 0
	ds_read_b128 v[24:27], v3
	ds_read_b128 v[28:31], v3 offset:16
	ds_read_b128 v[32:35], v3 offset:4096
	ds_read_b128 v[36:39], v3 offset:4112
	ds_read_b128 v[40:43], v3 offset:8192
	ds_read_b128 v[44:47], v3 offset:8208
	ds_read_b128 v[48:51], v3 offset:12288
	ds_read_b128 v[52:55], v3 offset:12304
	ds_read_b128 v[56:59], v3 offset:32
	ds_read_b128 v[60:63], v3 offset:48
	ds_read_b128 v[64:67], v3 offset:4128
	ds_read_b128 v[68:71], v3 offset:4144
	ds_read_b128 v[72:75], v3 offset:8224
	ds_read_b128 v[76:79], v3 offset:8240
	ds_read_b128 v[80:83], v3 offset:12320
	ds_read_b128 v[84:87], v3 offset:12336
	s_waitcnt vmcnt(24)
	s_waitcnt lgkmcnt(8)
	v_fmac_f32_e32 v12, v100, v24
	v_fmac_f32_e32 v13, v100, v32
	v_fmac_f32_e32 v14, v100, v40
	v_fmac_f32_e32 v15, v100, v48
	v_fmac_f32_e32 v12, v101, v25
	v_fmac_f32_e32 v13, v101, v33
	v_fmac_f32_e32 v14, v101, v41
	v_fmac_f32_e32 v15, v101, v49
	v_fmac_f32_e32 v12, v102, v26
	v_fmac_f32_e32 v13, v102, v34
	v_fmac_f32_e32 v14, v102, v42
	v_fmac_f32_e32 v15, v102, v50
	v_fmac_f32_e32 v12, v103, v27
	v_fmac_f32_e32 v13, v103, v35
	v_fmac_f32_e32 v14, v103, v43
	v_fmac_f32_e32 v15, v103, v51
	v_fmac_f32_e32 v12, v104, v28
	v_fmac_f32_e32 v13, v104, v36
	v_fmac_f32_e32 v14, v104, v44
	v_fmac_f32_e32 v15, v104, v52
	v_fmac_f32_e32 v12, v105, v29
	v_fmac_f32_e32 v13, v105, v37
	v_fmac_f32_e32 v14, v105, v45
	v_fmac_f32_e32 v15, v105, v53
	v_fmac_f32_e32 v12, v106, v30
	v_fmac_f32_e32 v13, v106, v38
	v_fmac_f32_e32 v14, v106, v46
	v_fmac_f32_e32 v15, v106, v54
	v_fmac_f32_e32 v12, v107, v31
	v_fmac_f32_e32 v13, v107, v39
	v_fmac_f32_e32 v14, v107, v47
	v_fmac_f32_e32 v15, v107, v55
	global_load_dword v132, v88, s[8:9]
	s_add_u32 s8, s8, 0x3000
	s_addc_u32 s9, s9, 0
	global_load_dword v133, v88, s[8:9]
	s_add_u32 s8, s8, 0x3000
	s_addc_u32 s9, s9, 0
	global_load_dword v134, v88, s[8:9]
	s_add_u32 s8, s8, 0x3000
	s_addc_u32 s9, s9, 0
	global_load_dword v135, v88, s[8:9]
	s_add_u32 s8, s8, 0x3000
	s_addc_u32 s9, s9, 0
	global_load_dword v136, v88, s[8:9]
	s_add_u32 s8, s8, 0x3000
	s_addc_u32 s9, s9, 0
	global_load_dword v137, v88, s[8:9]
	s_add_u32 s8, s8, 0x3000
	s_addc_u32 s9, s9, 0
	global_load_dword v138, v88, s[8:9]
	s_add_u32 s8, s8, 0x3000
	s_addc_u32 s9, s9, 0
; __device__ __forceinline__ void p0_prologue(const Args& A, LAS unsigned char* lds) {
;     ...
; #pragma unroll 8
;         for (int k = kc * 128; k < kc * 128 + 128; ++k) { const float wv = w[(size_t)k * 3072]; a0 += sc[k] * wv; a1 += sc[1024 + k] * wv; a2 += sc[2048 + k] * wv; a3 += sc[3072 + k] * wv; }
;         red[(kc * 4 + 0) * 64 + (tid & 63)] = a0; red[(kc * 4 + 1) * 64 + (tid & 63)] = a1; red[(kc * 4 + 2) * 64 + (tid & 63)] = a2; red[(kc * 4 + 3) * 64 + (tid & 63)] = a3;
	global_load_dword v139, v88, s[8:9]
	s_add_u32 s8, s8, 0x3000
	s_addc_u32 s9, s9, 0
	global_load_dword v140, v88, s[8:9]
	s_add_u32 s8, s8, 0x3000
	s_addc_u32 s9, s9, 0
	global_load_dword v141, v88, s[8:9]
	s_add_u32 s8, s8, 0x3000
	s_addc_u32 s9, s9, 0
	global_load_dword v142, v88, s[8:9]
	s_add_u32 s8, s8, 0x3000
	s_addc_u32 s9, s9, 0
	global_load_dword v143, v88, s[8:9]
	s_add_u32 s8, s8, 0x3000
	s_addc_u32 s9, s9, 0
	global_load_dword v144, v88, s[8:9]
	s_add_u32 s8, s8, 0x3000
	s_addc_u32 s9, s9, 0
	global_load_dword v145, v88, s[8:9]
	s_add_u32 s8, s8, 0x3000
	s_addc_u32 s9, s9, 0
	global_load_dword v146, v88, s[8:9]
	s_add_u32 s8, s8, 0x3000
	s_addc_u32 s9, s9, 0
	global_load_dword v147, v88, s[8:9]
	s_add_u32 s8, s8, 0x3000
	s_addc_u32 s9, s9, 0
	global_load_dword v148, v88, s[8:9]
	s_add_u32 s8, s8, 0x3000
	s_addc_u32 s9, s9, 0
	global_load_dword v149, v88, s[8:9]
	s_add_u32 s8, s8, 0x3000
	s_addc_u32 s9, s9, 0
	global_load_dword v150, v88, s[8:9]
	s_add_u32 s8, s8, 0x3000
	s_addc_u32 s9, s9, 0
	global_load_dword v151, v88, s[8:9]
	s_add_u32 s8, s8, 0x3000
	s_addc_u32 s9, s9, 0
	global_load_dword v152, v88, s[8:9]
	s_add_u32 s8, s8, 0x3000
	s_addc_u32 s9, s9, 0
	global_load_dword v153, v88, s[8:9]
	s_add_u32 s8, s8, 0x3000
	s_addc_u32 s9, s9, 0
	global_load_dword v154, v88, s[8:9]
	s_add_u32 s8, s8, 0x3000
	s_addc_u32 s9, s9, 0
	global_load_dword v155, v88, s[8:9]
	s_add_u32 s8, s8, 0x3000
	s_addc_u32 s9, s9, 0
	global_load_dword v156, v88, s[8:9]
	s_add_u32 s8, s8, 0x3000
	s_addc_u32 s9, s9, 0
	global_load_dword v157, v88, s[8:9]
	s_add_u32 s8, s8, 0x3000
	s_addc_u32 s9, s9, 0
	global_load_dword v158, v88, s[8:9]
	s_add_u32 s8, s8, 0x3000
	s_addc_u32 s9, s9, 0
	global_load_dword v159, v88, s[8:9]
	s_add_u32 s8, s8, 0x3000
	s_addc_u32 s9, s9, 0
	global_load_dword v160, v88, s[8:9]
	s_add_u32 s8, s8, 0x3000
	s_addc_u32 s9, s9, 0
	global_load_dword v161, v88, s[8:9]
	s_add_u32 s8, s8, 0x3000
	s_addc_u32 s9, s9, 0
	global_load_dword v162, v88, s[8:9]
	s_add_u32 s8, s8, 0x3000
	s_addc_u32 s9, s9, 0
	global_load_dword v163, v88, s[8:9]
	s_add_u32 s8, s8, 0x3000
	s_addc_u32 s9, s9, 0
	ds_read_b128 v[24:27], v3 offset:64
	ds_read_b128 v[28:31], v3 offset:80
	ds_read_b128 v[32:35], v3 offset:4160
	ds_read_b128 v[36:39], v3 offset:4176
	ds_read_b128 v[40:43], v3 offset:8256
	ds_read_b128 v[44:47], v3 offset:8272
	ds_read_b128 v[48:51], v3 offset:12352
	ds_read_b128 v[52:55], v3 offset:12368
	s_waitcnt vmcnt(48)
	s_waitcnt lgkmcnt(8)
	v_fmac_f32_e32 v12, v108, v56
	v_fmac_f32_e32 v13, v108, v64
	v_fmac_f32_e32 v14, v108, v72
	v_fmac_f32_e32 v15, v108, v80
	v_fmac_f32_e32 v12, v109, v57
	v_fmac_f32_e32 v13, v109, v65
	v_fmac_f32_e32 v14, v109, v73
	v_fmac_f32_e32 v15, v109, v81
	v_fmac_f32_e32 v12, v110, v58
	v_fmac_f32_e32 v13, v110, v66
	v_fmac_f32_e32 v14, v110, v74
	v_fmac_f32_e32 v15, v110, v82
	v_fmac_f32_e32 v12, v111, v59
	v_fmac_f32_e32 v13, v111, v67
	v_fmac_f32_e32 v14, v111, v75
	v_fmac_f32_e32 v15, v111, v83
	v_fmac_f32_e32 v12, v112, v60
	v_fmac_f32_e32 v13, v112, v68
	v_fmac_f32_e32 v14, v112, v76
	v_fmac_f32_e32 v15, v112, v84
	v_fmac_f32_e32 v12, v113, v61
	v_fmac_f32_e32 v13, v113, v69
	v_fmac_f32_e32 v14, v113, v77
	v_fmac_f32_e32 v15, v113, v85
	v_fmac_f32_e32 v12, v114, v62
	v_fmac_f32_e32 v13, v114, v70
	v_fmac_f32_e32 v14, v114, v78
	v_fmac_f32_e32 v15, v114, v86
	v_fmac_f32_e32 v12, v115, v63
	v_fmac_f32_e32 v13, v115, v71
	v_fmac_f32_e32 v14, v115, v79
	v_fmac_f32_e32 v15, v115, v87
	ds_read_b128 v[56:59], v3 offset:96
	ds_read_b128 v[60:63], v3 offset:112
	ds_read_b128 v[64:67], v3 offset:4192
	ds_read_b128 v[68:71], v3 offset:4208
	ds_read_b128 v[72:75], v3 offset:8288
	ds_read_b128 v[76:79], v3 offset:8304
	ds_read_b128 v[80:83], v3 offset:12384
	ds_read_b128 v[84:87], v3 offset:12400
	s_waitcnt vmcnt(40)
	s_waitcnt lgkmcnt(8)
	v_fmac_f32_e32 v12, v116, v24
	v_fmac_f32_e32 v13, v116, v32
	v_fmac_f32_e32 v14, v116, v40
	v_fmac_f32_e32 v15, v116, v48
	v_fmac_f32_e32 v12, v117, v25
	v_fmac_f32_e32 v13, v117, v33
	v_fmac_f32_e32 v14, v117, v41
	v_fmac_f32_e32 v15, v117, v49
	v_fmac_f32_e32 v12, v118, v26
	v_fmac_f32_e32 v13, v118, v34
	v_fmac_f32_e32 v14, v118, v42
	v_fmac_f32_e32 v15, v118, v50
	v_fmac_f32_e32 v12, v119, v27
	v_fmac_f32_e32 v13, v119, v35
	v_fmac_f32_e32 v14, v119, v43
	v_fmac_f32_e32 v15, v119, v51
	v_fmac_f32_e32 v12, v120, v28
	v_fmac_f32_e32 v13, v120, v36
	v_fmac_f32_e32 v14, v120, v44
	v_fmac_f32_e32 v15, v120, v52
	v_fmac_f32_e32 v12, v121, v29
	v_fmac_f32_e32 v13, v121, v37
	v_fmac_f32_e32 v14, v121, v45
	v_fmac_f32_e32 v15, v121, v53
	v_fmac_f32_e32 v12, v122, v30
	v_fmac_f32_e32 v13, v122, v38
	v_fmac_f32_e32 v14, v122, v46
	v_fmac_f32_e32 v15, v122, v54
	v_fmac_f32_e32 v12, v123, v31
	v_fmac_f32_e32 v13, v123, v39
	v_fmac_f32_e32 v14, v123, v47
	v_fmac_f32_e32 v15, v123, v55
	ds_read_b128 v[24:27], v3 offset:128
	ds_read_b128 v[28:31], v3 offset:144
	ds_read_b128 v[32:35], v3 offset:4224
	ds_read_b128 v[36:39], v3 offset:4240
	ds_read_b128 v[40:43], v3 offset:8320
	ds_read_b128 v[44:47], v3 offset:8336
	ds_read_b128 v[48:51], v3 offset:12416
	ds_read_b128 v[52:55], v3 offset:12432
	s_waitcnt vmcnt(32)
	s_waitcnt lgkmcnt(8)
; __device__ __forceinline__ void p0_prologue(const Args& A, LAS unsigned char* lds) {
;     ...
; #pragma unroll 8
;         for (int k = kc * 128; k < kc * 128 + 128; ++k) { const float wv = w[(size_t)k * 3072]; a0 += sc[k] * wv; a1 += sc[1024 + k] * wv; a2 += sc[2048 + k] * wv; a3 += sc[3072 + k] * wv; }
;         red[(kc * 4 + 0) * 64 + (tid & 63)] = a0; red[(kc * 4 + 1) * 64 + (tid & 63)] = a1; red[(kc * 4 + 2) * 64 + (tid & 63)] = a2; red[(kc * 4 + 3) * 64 + (tid & 63)] = a3;
	v_fmac_f32_e32 v12, v124, v56
	v_fmac_f32_e32 v13, v124, v64
	v_fmac_f32_e32 v14, v124, v72
	v_fmac_f32_e32 v15, v124, v80
	v_fmac_f32_e32 v12, v125, v57
	v_fmac_f32_e32 v13, v125, v65
	v_fmac_f32_e32 v14, v125, v73
	v_fmac_f32_e32 v15, v125, v81
	v_fmac_f32_e32 v12, v126, v58
	v_fmac_f32_e32 v13, v126, v66
	v_fmac_f32_e32 v14, v126, v74
	v_fmac_f32_e32 v15, v126, v82
	v_fmac_f32_e32 v12, v127, v59
	v_fmac_f32_e32 v13, v127, v67
	v_fmac_f32_e32 v14, v127, v75
	v_fmac_f32_e32 v15, v127, v83
	v_fmac_f32_e32 v12, v128, v60
	v_fmac_f32_e32 v13, v128, v68
	v_fmac_f32_e32 v14, v128, v76
	v_fmac_f32_e32 v15, v128, v84
	v_fmac_f32_e32 v12, v129, v61
	v_fmac_f32_e32 v13, v129, v69
	v_fmac_f32_e32 v14, v129, v77
	v_fmac_f32_e32 v15, v129, v85
	v_fmac_f32_e32 v12, v130, v62
	v_fmac_f32_e32 v13, v130, v70
	v_fmac_f32_e32 v14, v130, v78
	v_fmac_f32_e32 v15, v130, v86
	v_fmac_f32_e32 v12, v131, v63
	v_fmac_f32_e32 v13, v131, v71
	v_fmac_f32_e32 v14, v131, v79
	v_fmac_f32_e32 v15, v131, v87
	ds_read_b128 v[56:59], v3 offset:160
	ds_read_b128 v[60:63], v3 offset:176
	ds_read_b128 v[64:67], v3 offset:4256
	ds_read_b128 v[68:71], v3 offset:4272
	ds_read_b128 v[72:75], v3 offset:8352
	ds_read_b128 v[76:79], v3 offset:8368
	ds_read_b128 v[80:83], v3 offset:12448
	ds_read_b128 v[84:87], v3 offset:12464
	s_waitcnt vmcnt(24)
	s_waitcnt lgkmcnt(8)
	v_fmac_f32_e32 v12, v132, v24
	v_fmac_f32_e32 v13, v132, v32
	v_fmac_f32_e32 v14, v132, v40
	v_fmac_f32_e32 v15, v132, v48
	v_fmac_f32_e32 v12, v133, v25
	v_fmac_f32_e32 v13, v133, v33
	v_fmac_f32_e32 v14, v133, v41
	v_fmac_f32_e32 v15, v133, v49
	v_fmac_f32_e32 v12, v134, v26
	v_fmac_f32_e32 v13, v134, v34
	v_fmac_f32_e32 v14, v134, v42
	v_fmac_f32_e32 v15, v134, v50
	v_fmac_f32_e32 v12, v135, v27
	v_fmac_f32_e32 v13, v135, v35
	v_fmac_f32_e32 v14, v135, v43
	v_fmac_f32_e32 v15, v135, v51
	v_fmac_f32_e32 v12, v136, v28
	v_fmac_f32_e32 v13, v136, v36
	v_fmac_f32_e32 v14, v136, v44
	v_fmac_f32_e32 v15, v136, v52
	v_fmac_f32_e32 v12, v137, v29
	v_fmac_f32_e32 v13, v137, v37
	v_fmac_f32_e32 v14, v137, v45
	v_fmac_f32_e32 v15, v137, v53
	v_fmac_f32_e32 v12, v138, v30
	v_fmac_f32_e32 v13, v138, v38
	v_fmac_f32_e32 v14, v138, v46
	v_fmac_f32_e32 v15, v138, v54
	v_fmac_f32_e32 v12, v139, v31
	v_fmac_f32_e32 v13, v139, v39
	v_fmac_f32_e32 v14, v139, v47
	v_fmac_f32_e32 v15, v139, v55
	global_load_dword v100, v88, s[8:9]
	s_add_u32 s8, s8, 0x3000
	s_addc_u32 s9, s9, 0
	global_load_dword v101, v88, s[8:9]
	s_add_u32 s8, s8, 0x3000
	s_addc_u32 s9, s9, 0
	global_load_dword v102, v88, s[8:9]
	s_add_u32 s8, s8, 0x3000
	s_addc_u32 s9, s9, 0
	global_load_dword v103, v88, s[8:9]
	s_add_u32 s8, s8, 0x3000
	s_addc_u32 s9, s9, 0
	global_load_dword v104, v88, s[8:9]
	s_add_u32 s8, s8, 0x3000
	s_addc_u32 s9, s9, 0
	global_load_dword v105, v88, s[8:9]
	s_add_u32 s8, s8, 0x3000
	s_addc_u32 s9, s9, 0
	global_load_dword v106, v88, s[8:9]
	s_add_u32 s8, s8, 0x3000
	s_addc_u32 s9, s9, 0
	global_load_dword v107, v88, s[8:9]
	s_add_u32 s8, s8, 0x3000
	s_addc_u32 s9, s9, 0
	global_load_dword v108, v88, s[8:9]
	s_add_u32 s8, s8, 0x3000
	s_addc_u32 s9, s9, 0
	global_load_dword v109, v88, s[8:9]
	s_add_u32 s8, s8, 0x3000
	s_addc_u32 s9, s9, 0
	global_load_dword v110, v88, s[8:9]
	s_add_u32 s8, s8, 0x3000
	s_addc_u32 s9, s9, 0
	global_load_dword v111, v88, s[8:9]
	s_add_u32 s8, s8, 0x3000
	s_addc_u32 s9, s9, 0
	global_load_dword v112, v88, s[8:9]
	s_add_u32 s8, s8, 0x3000
	s_addc_u32 s9, s9, 0
	global_load_dword v113, v88, s[8:9]
	s_add_u32 s8, s8, 0x3000
	s_addc_u32 s9, s9, 0
	global_load_dword v114, v88, s[8:9]
	s_add_u32 s8, s8, 0x3000
	s_addc_u32 s9, s9, 0
	global_load_dword v115, v88, s[8:9]
	s_add_u32 s8, s8, 0x3000
	s_addc_u32 s9, s9, 0
	global_load_dword v116, v88, s[8:9]
	s_add_u32 s8, s8, 0x3000
	s_addc_u32 s9, s9, 0
	global_load_dword v117, v88, s[8:9]
	s_add_u32 s8, s8, 0x3000
	s_addc_u32 s9, s9, 0
	global_load_dword v118, v88, s[8:9]
	s_add_u32 s8, s8, 0x3000
	s_addc_u32 s9, s9, 0
	global_load_dword v119, v88, s[8:9]
	s_add_u32 s8, s8, 0x3000
	s_addc_u32 s9, s9, 0
	global_load_dword v120, v88, s[8:9]
	s_add_u32 s8, s8, 0x3000
	s_addc_u32 s9, s9, 0
	global_load_dword v121, v88, s[8:9]
	s_add_u32 s8, s8, 0x3000
	s_addc_u32 s9, s9, 0
	global_load_dword v122, v88, s[8:9]
	s_add_u32 s8, s8, 0x3000
	s_addc_u32 s9, s9, 0
	global_load_dword v123, v88, s[8:9]
	s_add_u32 s8, s8, 0x3000
	s_addc_u32 s9, s9, 0
	global_load_dword v124, v88, s[8:9]
	s_add_u32 s8, s8, 0x3000
	s_addc_u32 s9, s9, 0
	global_load_dword v125, v88, s[8:9]
	s_add_u32 s8, s8, 0x3000
	s_addc_u32 s9, s9, 0
	global_load_dword v126, v88, s[8:9]
	s_add_u32 s8, s8, 0x3000
	s_addc_u32 s9, s9, 0
	global_load_dword v127, v88, s[8:9]
	s_add_u32 s8, s8, 0x3000
	s_addc_u32 s9, s9, 0
	global_load_dword v128, v88, s[8:9]
	s_add_u32 s8, s8, 0x3000
	s_addc_u32 s9, s9, 0
	global_load_dword v129, v88, s[8:9]
	s_add_u32 s8, s8, 0x3000
	s_addc_u32 s9, s9, 0
	global_load_dword v130, v88, s[8:9]
	s_add_u32 s8, s8, 0x3000
	s_addc_u32 s9, s9, 0
	global_load_dword v131, v88, s[8:9]
	s_add_u32 s8, s8, 0x3000
	s_addc_u32 s9, s9, 0
	ds_read_b128 v[24:27], v3 offset:192
	ds_read_b128 v[28:31], v3 offset:208
	ds_read_b128 v[32:35], v3 offset:4288
	ds_read_b128 v[36:39], v3 offset:4304
	ds_read_b128 v[40:43], v3 offset:8384
	ds_read_b128 v[44:47], v3 offset:8400
	ds_read_b128 v[48:51], v3 offset:12480
	ds_read_b128 v[52:55], v3 offset:12496
	s_waitcnt vmcnt(48)
	s_waitcnt lgkmcnt(8)
; __device__ __forceinline__ void p0_prologue(const Args& A, LAS unsigned char* lds) {
;     ...
; #pragma unroll 8
;         for (int k = kc * 128; k < kc * 128 + 128; ++k) { const float wv = w[(size_t)k * 3072]; a0 += sc[k] * wv; a1 += sc[1024 + k] * wv; a2 += sc[2048 + k] * wv; a3 += sc[3072 + k] * wv; }
;         red[(kc * 4 + 0) * 64 + (tid & 63)] = a0; red[(kc * 4 + 1) * 64 + (tid & 63)] = a1; red[(kc * 4 + 2) * 64 + (tid & 63)] = a2; red[(kc * 4 + 3) * 64 + (tid & 63)] = a3;
	v_fmac_f32_e32 v12, v140, v56
	v_fmac_f32_e32 v13, v140, v64
	v_fmac_f32_e32 v14, v140, v72
	v_fmac_f32_e32 v15, v140, v80
	v_fmac_f32_e32 v12, v141, v57
	v_fmac_f32_e32 v13, v141, v65
	v_fmac_f32_e32 v14, v141, v73
	v_fmac_f32_e32 v15, v141, v81
	v_fmac_f32_e32 v12, v142, v58
	v_fmac_f32_e32 v13, v142, v66
	v_fmac_f32_e32 v14, v142, v74
	v_fmac_f32_e32 v15, v142, v82
	v_fmac_f32_e32 v12, v143, v59
	v_fmac_f32_e32 v13, v143, v67
	v_fmac_f32_e32 v14, v143, v75
	v_fmac_f32_e32 v15, v143, v83
	v_fmac_f32_e32 v12, v144, v60
	v_fmac_f32_e32 v13, v144, v68
	v_fmac_f32_e32 v14, v144, v76
	v_fmac_f32_e32 v15, v144, v84
	v_fmac_f32_e32 v12, v145, v61
	v_fmac_f32_e32 v13, v145, v69
	v_fmac_f32_e32 v14, v145, v77
	v_fmac_f32_e32 v15, v145, v85
	v_fmac_f32_e32 v12, v146, v62
	v_fmac_f32_e32 v13, v146, v70
	v_fmac_f32_e32 v14, v146, v78
	v_fmac_f32_e32 v15, v146, v86
	v_fmac_f32_e32 v12, v147, v63
	v_fmac_f32_e32 v13, v147, v71
	v_fmac_f32_e32 v14, v147, v79
	v_fmac_f32_e32 v15, v147, v87
	ds_read_b128 v[56:59], v3 offset:224
	ds_read_b128 v[60:63], v3 offset:240
	ds_read_b128 v[64:67], v3 offset:4320
	ds_read_b128 v[68:71], v3 offset:4336
	ds_read_b128 v[72:75], v3 offset:8416
	ds_read_b128 v[76:79], v3 offset:8432
	ds_read_b128 v[80:83], v3 offset:12512
	ds_read_b128 v[84:87], v3 offset:12528
	s_waitcnt vmcnt(40)
	s_waitcnt lgkmcnt(8)
	v_fmac_f32_e32 v12, v148, v24
	v_fmac_f32_e32 v13, v148, v32
	v_fmac_f32_e32 v14, v148, v40
	v_fmac_f32_e32 v15, v148, v48
	v_fmac_f32_e32 v12, v149, v25
	v_fmac_f32_e32 v13, v149, v33
	v_fmac_f32_e32 v14, v149, v41
	v_fmac_f32_e32 v15, v149, v49
	v_fmac_f32_e32 v12, v150, v26
	v_fmac_f32_e32 v13, v150, v34
	v_fmac_f32_e32 v14, v150, v42
	v_fmac_f32_e32 v15, v150, v50
	v_fmac_f32_e32 v12, v151, v27
	v_fmac_f32_e32 v13, v151, v35
	v_fmac_f32_e32 v14, v151, v43
	v_fmac_f32_e32 v15, v151, v51
	v_fmac_f32_e32 v12, v152, v28
	v_fmac_f32_e32 v13, v152, v36
	v_fmac_f32_e32 v14, v152, v44
	v_fmac_f32_e32 v15, v152, v52
	v_fmac_f32_e32 v12, v153, v29
	v_fmac_f32_e32 v13, v153, v37
	v_fmac_f32_e32 v14, v153, v45
	v_fmac_f32_e32 v15, v153, v53
	v_fmac_f32_e32 v12, v154, v30
	v_fmac_f32_e32 v13, v154, v38
	v_fmac_f32_e32 v14, v154, v46
	v_fmac_f32_e32 v15, v154, v54
	v_fmac_f32_e32 v12, v155, v31
	v_fmac_f32_e32 v13, v155, v39
	v_fmac_f32_e32 v14, v155, v47
	v_fmac_f32_e32 v15, v155, v55
	ds_read_b128 v[24:27], v3 offset:256
	ds_read_b128 v[28:31], v3 offset:272
	ds_read_b128 v[32:35], v3 offset:4352
	ds_read_b128 v[36:39], v3 offset:4368
	ds_read_b128 v[40:43], v3 offset:8448
	ds_read_b128 v[44:47], v3 offset:8464
	ds_read_b128 v[48:51], v3 offset:12544
	ds_read_b128 v[52:55], v3 offset:12560
	s_waitcnt vmcnt(32)
	s_waitcnt lgkmcnt(8)
	v_fmac_f32_e32 v12, v156, v56
	v_fmac_f32_e32 v13, v156, v64
	v_fmac_f32_e32 v14, v156, v72
	v_fmac_f32_e32 v15, v156, v80
	v_fmac_f32_e32 v12, v157, v57
	v_fmac_f32_e32 v13, v157, v65
	v_fmac_f32_e32 v14, v157, v73
	v_fmac_f32_e32 v15, v157, v81
	v_fmac_f32_e32 v12, v158, v58
	v_fmac_f32_e32 v13, v158, v66
	v_fmac_f32_e32 v14, v158, v74
	v_fmac_f32_e32 v15, v158, v82
	v_fmac_f32_e32 v12, v159, v59
	v_fmac_f32_e32 v13, v159, v67
	v_fmac_f32_e32 v14, v159, v75
	v_fmac_f32_e32 v15, v159, v83
	v_fmac_f32_e32 v12, v160, v60
	v_fmac_f32_e32 v13, v160, v68
	v_fmac_f32_e32 v14, v160, v76
	v_fmac_f32_e32 v15, v160, v84
	v_fmac_f32_e32 v12, v161, v61
	v_fmac_f32_e32 v13, v161, v69
	v_fmac_f32_e32 v14, v161, v77
	v_fmac_f32_e32 v15, v161, v85
	v_fmac_f32_e32 v12, v162, v62
	v_fmac_f32_e32 v13, v162, v70
	v_fmac_f32_e32 v14, v162, v78
	v_fmac_f32_e32 v15, v162, v86
	v_fmac_f32_e32 v12, v163, v63
	v_fmac_f32_e32 v13, v163, v71
	v_fmac_f32_e32 v14, v163, v79
	v_fmac_f32_e32 v15, v163, v87
	ds_read_b128 v[56:59], v3 offset:288
	ds_read_b128 v[60:63], v3 offset:304
	ds_read_b128 v[64:67], v3 offset:4384
	ds_read_b128 v[68:71], v3 offset:4400
	ds_read_b128 v[72:75], v3 offset:8480
	ds_read_b128 v[76:79], v3 offset:8496
	ds_read_b128 v[80:83], v3 offset:12576
	ds_read_b128 v[84:87], v3 offset:12592
	s_waitcnt vmcnt(24)
	s_waitcnt lgkmcnt(8)
	v_fmac_f32_e32 v12, v100, v24
	v_fmac_f32_e32 v13, v100, v32
	v_fmac_f32_e32 v14, v100, v40
	v_fmac_f32_e32 v15, v100, v48
	v_fmac_f32_e32 v12, v101, v25
	v_fmac_f32_e32 v13, v101, v33
	v_fmac_f32_e32 v14, v101, v41
	v_fmac_f32_e32 v15, v101, v49
	v_fmac_f32_e32 v12, v102, v26
	v_fmac_f32_e32 v13, v102, v34
	v_fmac_f32_e32 v14, v102, v42
	v_fmac_f32_e32 v15, v102, v50
	v_fmac_f32_e32 v12, v103, v27
	v_fmac_f32_e32 v13, v103, v35
	v_fmac_f32_e32 v14, v103, v43
	v_fmac_f32_e32 v15, v103, v51
	v_fmac_f32_e32 v12, v104, v28
	v_fmac_f32_e32 v13, v104, v36
	v_fmac_f32_e32 v14, v104, v44
	v_fmac_f32_e32 v15, v104, v52
	v_fmac_f32_e32 v12, v105, v29
	v_fmac_f32_e32 v13, v105, v37
	v_fmac_f32_e32 v14, v105, v45
	v_fmac_f32_e32 v15, v105, v53
	v_fmac_f32_e32 v12, v106, v30
	v_fmac_f32_e32 v13, v106, v38
	v_fmac_f32_e32 v14, v106, v46
	v_fmac_f32_e32 v15, v106, v54
	v_fmac_f32_e32 v12, v107, v31
	v_fmac_f32_e32 v13, v107, v39
	v_fmac_f32_e32 v14, v107, v47
	v_fmac_f32_e32 v15, v107, v55
	global_load_dword v132, v88, s[8:9]
	s_add_u32 s8, s8, 0x3000
	s_addc_u32 s9, s9, 0
	global_load_dword v133, v88, s[8:9]
	s_add_u32 s8, s8, 0x3000
	s_addc_u32 s9, s9, 0
	global_load_dword v134, v88, s[8:9]
	s_add_u32 s8, s8, 0x3000
	s_addc_u32 s9, s9, 0
	global_load_dword v135, v88, s[8:9]
	s_add_u32 s8, s8, 0x3000
	s_addc_u32 s9, s9, 0
	global_load_dword v136, v88, s[8:9]
	s_add_u32 s8, s8, 0x3000
	s_addc_u32 s9, s9, 0
	global_load_dword v137, v88, s[8:9]
	s_add_u32 s8, s8, 0x3000
	s_addc_u32 s9, s9, 0
	global_load_dword v138, v88, s[8:9]
	s_add_u32 s8, s8, 0x3000
	s_addc_u32 s9, s9, 0
; __device__ __forceinline__ void p0_prologue(const Args& A, LAS unsigned char* lds) {
;     ...
; #pragma unroll 8
;         for (int k = kc * 128; k < kc * 128 + 128; ++k) { const float wv = w[(size_t)k * 3072]; a0 += sc[k] * wv; a1 += sc[1024 + k] * wv; a2 += sc[2048 + k] * wv; a3 += sc[3072 + k] * wv; }
;         red[(kc * 4 + 0) * 64 + (tid & 63)] = a0; red[(kc * 4 + 1) * 64 + (tid & 63)] = a1; red[(kc * 4 + 2) * 64 + (tid & 63)] = a2; red[(kc * 4 + 3) * 64 + (tid & 63)] = a3;
	global_load_dword v139, v88, s[8:9]
	s_add_u32 s8, s8, 0x3000
	s_addc_u32 s9, s9, 0
	global_load_dword v140, v88, s[8:9]
	s_add_u32 s8, s8, 0x3000
	s_addc_u32 s9, s9, 0
	global_load_dword v141, v88, s[8:9]
	s_add_u32 s8, s8, 0x3000
	s_addc_u32 s9, s9, 0
	global_load_dword v142, v88, s[8:9]
	s_add_u32 s8, s8, 0x3000
	s_addc_u32 s9, s9, 0
	global_load_dword v143, v88, s[8:9]
	s_add_u32 s8, s8, 0x3000
	s_addc_u32 s9, s9, 0
	global_load_dword v144, v88, s[8:9]
	s_add_u32 s8, s8, 0x3000
	s_addc_u32 s9, s9, 0
	global_load_dword v145, v88, s[8:9]
	s_add_u32 s8, s8, 0x3000
	s_addc_u32 s9, s9, 0
	global_load_dword v146, v88, s[8:9]
	s_add_u32 s8, s8, 0x3000
	s_addc_u32 s9, s9, 0
	global_load_dword v147, v88, s[8:9]
	s_add_u32 s8, s8, 0x3000
	s_addc_u32 s9, s9, 0
	global_load_dword v148, v88, s[8:9]
	s_add_u32 s8, s8, 0x3000
	s_addc_u32 s9, s9, 0
	global_load_dword v149, v88, s[8:9]
	s_add_u32 s8, s8, 0x3000
	s_addc_u32 s9, s9, 0
	global_load_dword v150, v88, s[8:9]
	s_add_u32 s8, s8, 0x3000
	s_addc_u32 s9, s9, 0
	global_load_dword v151, v88, s[8:9]
	s_add_u32 s8, s8, 0x3000
	s_addc_u32 s9, s9, 0
	global_load_dword v152, v88, s[8:9]
	s_add_u32 s8, s8, 0x3000
	s_addc_u32 s9, s9, 0
	global_load_dword v153, v88, s[8:9]
	s_add_u32 s8, s8, 0x3000
	s_addc_u32 s9, s9, 0
	global_load_dword v154, v88, s[8:9]
	s_add_u32 s8, s8, 0x3000
	s_addc_u32 s9, s9, 0
	global_load_dword v155, v88, s[8:9]
	s_add_u32 s8, s8, 0x3000
	s_addc_u32 s9, s9, 0
	global_load_dword v156, v88, s[8:9]
	s_add_u32 s8, s8, 0x3000
	s_addc_u32 s9, s9, 0
	global_load_dword v157, v88, s[8:9]
	s_add_u32 s8, s8, 0x3000
	s_addc_u32 s9, s9, 0
	global_load_dword v158, v88, s[8:9]
	s_add_u32 s8, s8, 0x3000
	s_addc_u32 s9, s9, 0
	global_load_dword v159, v88, s[8:9]
	s_add_u32 s8, s8, 0x3000
	s_addc_u32 s9, s9, 0
	global_load_dword v160, v88, s[8:9]
	s_add_u32 s8, s8, 0x3000
	s_addc_u32 s9, s9, 0
	global_load_dword v161, v88, s[8:9]
	s_add_u32 s8, s8, 0x3000
	s_addc_u32 s9, s9, 0
	global_load_dword v162, v88, s[8:9]
	s_add_u32 s8, s8, 0x3000
	s_addc_u32 s9, s9, 0
	global_load_dword v163, v88, s[8:9]
	s_add_u32 s8, s8, 0x3000
	s_addc_u32 s9, s9, 0
	ds_read_b128 v[24:27], v3 offset:320
	ds_read_b128 v[28:31], v3 offset:336
	ds_read_b128 v[32:35], v3 offset:4416
	ds_read_b128 v[36:39], v3 offset:4432
	ds_read_b128 v[40:43], v3 offset:8512
	ds_read_b128 v[44:47], v3 offset:8528
	ds_read_b128 v[48:51], v3 offset:12608
	ds_read_b128 v[52:55], v3 offset:12624
	s_waitcnt vmcnt(48)
	s_waitcnt lgkmcnt(8)
	v_fmac_f32_e32 v12, v108, v56
	v_fmac_f32_e32 v13, v108, v64
	v_fmac_f32_e32 v14, v108, v72
	v_fmac_f32_e32 v15, v108, v80
	v_fmac_f32_e32 v12, v109, v57
	v_fmac_f32_e32 v13, v109, v65
	v_fmac_f32_e32 v14, v109, v73
	v_fmac_f32_e32 v15, v109, v81
	v_fmac_f32_e32 v12, v110, v58
	v_fmac_f32_e32 v13, v110, v66
	v_fmac_f32_e32 v14, v110, v74
	v_fmac_f32_e32 v15, v110, v82
	v_fmac_f32_e32 v12, v111, v59
	v_fmac_f32_e32 v13, v111, v67
	v_fmac_f32_e32 v14, v111, v75
	v_fmac_f32_e32 v15, v111, v83
	v_fmac_f32_e32 v12, v112, v60
	v_fmac_f32_e32 v13, v112, v68
	v_fmac_f32_e32 v14, v112, v76
	v_fmac_f32_e32 v15, v112, v84
	v_fmac_f32_e32 v12, v113, v61
	v_fmac_f32_e32 v13, v113, v69
	v_fmac_f32_e32 v14, v113, v77
	v_fmac_f32_e32 v15, v113, v85
	v_fmac_f32_e32 v12, v114, v62
	v_fmac_f32_e32 v13, v114, v70
	v_fmac_f32_e32 v14, v114, v78
	v_fmac_f32_e32 v15, v114, v86
	v_fmac_f32_e32 v12, v115, v63
	v_fmac_f32_e32 v13, v115, v71
	v_fmac_f32_e32 v14, v115, v79
	v_fmac_f32_e32 v15, v115, v87
	ds_read_b128 v[56:59], v3 offset:352
	ds_read_b128 v[60:63], v3 offset:368
	ds_read_b128 v[64:67], v3 offset:4448
	ds_read_b128 v[68:71], v3 offset:4464
	ds_read_b128 v[72:75], v3 offset:8544
	ds_read_b128 v[76:79], v3 offset:8560
	ds_read_b128 v[80:83], v3 offset:12640
	ds_read_b128 v[84:87], v3 offset:12656
	s_waitcnt vmcnt(40)
	s_waitcnt lgkmcnt(8)
	v_fmac_f32_e32 v12, v116, v24
	v_fmac_f32_e32 v13, v116, v32
	v_fmac_f32_e32 v14, v116, v40
	v_fmac_f32_e32 v15, v116, v48
	v_fmac_f32_e32 v12, v117, v25
	v_fmac_f32_e32 v13, v117, v33
	v_fmac_f32_e32 v14, v117, v41
	v_fmac_f32_e32 v15, v117, v49
	v_fmac_f32_e32 v12, v118, v26
	v_fmac_f32_e32 v13, v118, v34
	v_fmac_f32_e32 v14, v118, v42
	v_fmac_f32_e32 v15, v118, v50
	v_fmac_f32_e32 v12, v119, v27
	v_fmac_f32_e32 v13, v119, v35
	v_fmac_f32_e32 v14, v119, v43
	v_fmac_f32_e32 v15, v119, v51
	v_fmac_f32_e32 v12, v120, v28
	v_fmac_f32_e32 v13, v120, v36
	v_fmac_f32_e32 v14, v120, v44
	v_fmac_f32_e32 v15, v120, v52
	v_fmac_f32_e32 v12, v121, v29
	v_fmac_f32_e32 v13, v121, v37
	v_fmac_f32_e32 v14, v121, v45
	v_fmac_f32_e32 v15, v121, v53
	v_fmac_f32_e32 v12, v122, v30
	v_fmac_f32_e32 v13, v122, v38
	v_fmac_f32_e32 v14, v122, v46
	v_fmac_f32_e32 v15, v122, v54
	v_fmac_f32_e32 v12, v123, v31
	v_fmac_f32_e32 v13, v123, v39
	v_fmac_f32_e32 v14, v123, v47
	v_fmac_f32_e32 v15, v123, v55
	ds_read_b128 v[24:27], v3 offset:384
	ds_read_b128 v[28:31], v3 offset:400
	ds_read_b128 v[32:35], v3 offset:4480
	ds_read_b128 v[36:39], v3 offset:4496
	ds_read_b128 v[40:43], v3 offset:8576
	ds_read_b128 v[44:47], v3 offset:8592
	ds_read_b128 v[48:51], v3 offset:12672
	ds_read_b128 v[52:55], v3 offset:12688
	s_waitcnt vmcnt(32)
	s_waitcnt lgkmcnt(8)
; __device__ __forceinline__ void p0_prologue(const Args& A, LAS unsigned char* lds) {
;     ...
; #pragma unroll 8
;         for (int k = kc * 128; k < kc * 128 + 128; ++k) { const float wv = w[(size_t)k * 3072]; a0 += sc[k] * wv; a1 += sc[1024 + k] * wv; a2 += sc[2048 + k] * wv; a3 += sc[3072 + k] * wv; }
;         red[(kc * 4 + 0) * 64 + (tid & 63)] = a0; red[(kc * 4 + 1) * 64 + (tid & 63)] = a1; red[(kc * 4 + 2) * 64 + (tid & 63)] = a2; red[(kc * 4 + 3) * 64 + (tid & 63)] = a3;
;         __syncthreads();
	v_fmac_f32_e32 v12, v124, v56
	v_fmac_f32_e32 v13, v124, v64
	v_fmac_f32_e32 v14, v124, v72
	v_fmac_f32_e32 v15, v124, v80
	v_fmac_f32_e32 v12, v125, v57
	v_fmac_f32_e32 v13, v125, v65
	v_fmac_f32_e32 v14, v125, v73
	v_fmac_f32_e32 v15, v125, v81
	v_fmac_f32_e32 v12, v126, v58
	v_fmac_f32_e32 v13, v126, v66
	v_fmac_f32_e32 v14, v126, v74
	v_fmac_f32_e32 v15, v126, v82
	v_fmac_f32_e32 v12, v127, v59
	v_fmac_f32_e32 v13, v127, v67
	v_fmac_f32_e32 v14, v127, v75
	v_fmac_f32_e32 v15, v127, v83
	v_fmac_f32_e32 v12, v128, v60
	v_fmac_f32_e32 v13, v128, v68
	v_fmac_f32_e32 v14, v128, v76
	v_fmac_f32_e32 v15, v128, v84
	v_fmac_f32_e32 v12, v129, v61
	v_fmac_f32_e32 v13, v129, v69
	v_fmac_f32_e32 v14, v129, v77
	v_fmac_f32_e32 v15, v129, v85
	v_fmac_f32_e32 v12, v130, v62
	v_fmac_f32_e32 v13, v130, v70
	v_fmac_f32_e32 v14, v130, v78
	v_fmac_f32_e32 v15, v130, v86
	v_fmac_f32_e32 v12, v131, v63
	v_fmac_f32_e32 v13, v131, v71
	v_fmac_f32_e32 v14, v131, v79
	v_fmac_f32_e32 v15, v131, v87
	ds_read_b128 v[56:59], v3 offset:416
	ds_read_b128 v[60:63], v3 offset:432
	ds_read_b128 v[64:67], v3 offset:4512
	ds_read_b128 v[68:71], v3 offset:4528
	ds_read_b128 v[72:75], v3 offset:8608
	ds_read_b128 v[76:79], v3 offset:8624
	ds_read_b128 v[80:83], v3 offset:12704
	ds_read_b128 v[84:87], v3 offset:12720
	s_waitcnt vmcnt(24)
	s_waitcnt lgkmcnt(8)
	v_fmac_f32_e32 v12, v132, v24
	v_fmac_f32_e32 v13, v132, v32
	v_fmac_f32_e32 v14, v132, v40
	v_fmac_f32_e32 v15, v132, v48
	v_fmac_f32_e32 v12, v133, v25
	v_fmac_f32_e32 v13, v133, v33
	v_fmac_f32_e32 v14, v133, v41
	v_fmac_f32_e32 v15, v133, v49
	v_fmac_f32_e32 v12, v134, v26
	v_fmac_f32_e32 v13, v134, v34
	v_fmac_f32_e32 v14, v134, v42
	v_fmac_f32_e32 v15, v134, v50
	v_fmac_f32_e32 v12, v135, v27
	v_fmac_f32_e32 v13, v135, v35
	v_fmac_f32_e32 v14, v135, v43
	v_fmac_f32_e32 v15, v135, v51
	v_fmac_f32_e32 v12, v136, v28
	v_fmac_f32_e32 v13, v136, v36
	v_fmac_f32_e32 v14, v136, v44
	v_fmac_f32_e32 v15, v136, v52
	v_fmac_f32_e32 v12, v137, v29
	v_fmac_f32_e32 v13, v137, v37
	v_fmac_f32_e32 v14, v137, v45
	v_fmac_f32_e32 v15, v137, v53
	v_fmac_f32_e32 v12, v138, v30
	v_fmac_f32_e32 v13, v138, v38
	v_fmac_f32_e32 v14, v138, v46
	v_fmac_f32_e32 v15, v138, v54
	v_fmac_f32_e32 v12, v139, v31
	v_fmac_f32_e32 v13, v139, v39
	v_fmac_f32_e32 v14, v139, v47
	v_fmac_f32_e32 v15, v139, v55
	ds_read_b128 v[24:27], v3 offset:448
	ds_read_b128 v[28:31], v3 offset:464
	ds_read_b128 v[32:35], v3 offset:4544
	ds_read_b128 v[36:39], v3 offset:4560
	ds_read_b128 v[40:43], v3 offset:8640
	ds_read_b128 v[44:47], v3 offset:8656
	ds_read_b128 v[48:51], v3 offset:12736
	ds_read_b128 v[52:55], v3 offset:12752
	s_waitcnt vmcnt(16)
	s_waitcnt lgkmcnt(8)
	v_fmac_f32_e32 v12, v140, v56
	v_fmac_f32_e32 v13, v140, v64
	v_fmac_f32_e32 v14, v140, v72
	v_fmac_f32_e32 v15, v140, v80
	v_fmac_f32_e32 v12, v141, v57
	v_fmac_f32_e32 v13, v141, v65
	v_fmac_f32_e32 v14, v141, v73
	v_fmac_f32_e32 v15, v141, v81
	v_fmac_f32_e32 v12, v142, v58
	v_fmac_f32_e32 v13, v142, v66
	v_fmac_f32_e32 v14, v142, v74
	v_fmac_f32_e32 v15, v142, v82
	v_fmac_f32_e32 v12, v143, v59
	v_fmac_f32_e32 v13, v143, v67
	v_fmac_f32_e32 v14, v143, v75
	v_fmac_f32_e32 v15, v143, v83
	v_fmac_f32_e32 v12, v144, v60
	v_fmac_f32_e32 v13, v144, v68
	v_fmac_f32_e32 v14, v144, v76
	v_fmac_f32_e32 v15, v144, v84
	v_fmac_f32_e32 v12, v145, v61
	v_fmac_f32_e32 v13, v145, v69
	v_fmac_f32_e32 v14, v145, v77
	v_fmac_f32_e32 v15, v145, v85
	v_fmac_f32_e32 v12, v146, v62
	v_fmac_f32_e32 v13, v146, v70
	v_fmac_f32_e32 v14, v146, v78
	v_fmac_f32_e32 v15, v146, v86
	v_fmac_f32_e32 v12, v147, v63
	v_fmac_f32_e32 v13, v147, v71
	v_fmac_f32_e32 v14, v147, v79
	v_fmac_f32_e32 v15, v147, v87
	ds_read_b128 v[56:59], v3 offset:480
	ds_read_b128 v[60:63], v3 offset:496
	ds_read_b128 v[64:67], v3 offset:4576
	ds_read_b128 v[68:71], v3 offset:4592
	ds_read_b128 v[72:75], v3 offset:8672
	ds_read_b128 v[76:79], v3 offset:8688
	ds_read_b128 v[80:83], v3 offset:12768
	ds_read_b128 v[84:87], v3 offset:12784
	s_waitcnt vmcnt(8)
	s_waitcnt lgkmcnt(8)
	v_fmac_f32_e32 v12, v148, v24
	v_fmac_f32_e32 v13, v148, v32
	v_fmac_f32_e32 v14, v148, v40
	v_fmac_f32_e32 v15, v148, v48
	v_fmac_f32_e32 v12, v149, v25
	v_fmac_f32_e32 v13, v149, v33
	v_fmac_f32_e32 v14, v149, v41
	v_fmac_f32_e32 v15, v149, v49
	v_fmac_f32_e32 v12, v150, v26
	v_fmac_f32_e32 v13, v150, v34
	v_fmac_f32_e32 v14, v150, v42
	v_fmac_f32_e32 v15, v150, v50
	v_fmac_f32_e32 v12, v151, v27
	v_fmac_f32_e32 v13, v151, v35
	v_fmac_f32_e32 v14, v151, v43
	v_fmac_f32_e32 v15, v151, v51
	v_fmac_f32_e32 v12, v152, v28
	v_fmac_f32_e32 v13, v152, v36
	v_fmac_f32_e32 v14, v152, v44
	v_fmac_f32_e32 v15, v152, v52
	v_fmac_f32_e32 v12, v153, v29
	v_fmac_f32_e32 v13, v153, v37
	v_fmac_f32_e32 v14, v153, v45
	v_fmac_f32_e32 v15, v153, v53
	v_fmac_f32_e32 v12, v154, v30
	v_fmac_f32_e32 v13, v154, v38
	v_fmac_f32_e32 v14, v154, v46
	v_fmac_f32_e32 v15, v154, v54
	v_fmac_f32_e32 v12, v155, v31
	v_fmac_f32_e32 v13, v155, v39
	v_fmac_f32_e32 v14, v155, v47
	v_fmac_f32_e32 v15, v155, v55
	s_waitcnt vmcnt(0)
	s_waitcnt lgkmcnt(0)
	v_fmac_f32_e32 v12, v156, v56
	v_fmac_f32_e32 v13, v156, v64
	v_fmac_f32_e32 v14, v156, v72
	v_fmac_f32_e32 v15, v156, v80
	v_fmac_f32_e32 v12, v157, v57
	v_fmac_f32_e32 v13, v157, v65
	v_fmac_f32_e32 v14, v157, v73
	v_fmac_f32_e32 v15, v157, v81
	v_fmac_f32_e32 v12, v158, v58
	v_fmac_f32_e32 v13, v158, v66
	v_fmac_f32_e32 v14, v158, v74
	v_fmac_f32_e32 v15, v158, v82
	v_fmac_f32_e32 v12, v159, v59
	v_fmac_f32_e32 v13, v159, v67
	v_fmac_f32_e32 v14, v159, v75
	v_fmac_f32_e32 v15, v159, v83
	v_fmac_f32_e32 v12, v160, v60
	v_fmac_f32_e32 v13, v160, v68
	v_fmac_f32_e32 v14, v160, v76
	v_fmac_f32_e32 v15, v160, v84
	v_fmac_f32_e32 v12, v161, v61
	v_fmac_f32_e32 v13, v161, v69
	v_fmac_f32_e32 v14, v161, v77
	v_fmac_f32_e32 v15, v161, v85
	v_fmac_f32_e32 v12, v162, v62
	v_fmac_f32_e32 v13, v162, v70
	v_fmac_f32_e32 v14, v162, v78
	v_fmac_f32_e32 v15, v162, v86
	v_fmac_f32_e32 v12, v163, v63
	v_fmac_f32_e32 v13, v163, v71
	v_fmac_f32_e32 v14, v163, v79
	v_fmac_f32_e32 v15, v163, v87
	ds_write2st64_b32 v18, v12, v13 offset0:64 offset1:65
	ds_write2st64_b32 v18, v14, v15 offset0:66 offset1:67
	s_waitcnt lgkmcnt(0)
	s_barrier
; __device__ __forceinline__ void p0_prologue(const Args& A, LAS unsigned char* lds) {
;     ...
;         if (tid < 256) { const int b = tid >> 6, cl = tid & 63; float s = 0.f;
; #pragma unroll
;             for (int q = 0; q < 8; ++q) s += red[(q * 4 + b) * 64 + cl];
;             const int cc = (it % 48) * 64 + cl;
;             ((float*)(ws + WS_MOD))[(l * 4 + b) * 3072 + cc] = s + A.b_ada[l * 3072 + cc]; }
	s_and_saveexec_b64 s[8:9], s[4:5]
	s_cbranch_execz .LBB0_15
	s_mul_i32 s13, s12, 0xc00
	v_add_u32_e32 v10, s13, v8
	v_ashrrev_i32_e32 v11, 31, v10
	v_lshl_add_u64 v[10:11], v[10:11], 2, s[80:81]
	global_load_dword v23, v[10:11], off
	ds_read2st64_b32 v[10:11], v19 offset0:64 offset1:68
	ds_read2st64_b32 v[12:13], v19 offset0:72 offset1:76
	ds_read2st64_b32 v[14:15], v19 offset0:80 offset1:84
	ds_read2st64_b32 v[24:25], v19 offset0:88 offset1:92
	v_lshl_add_u32 v9, s12, 2, v17
	s_waitcnt lgkmcnt(3)
	v_add_f32_e32 v10, 0, v10
	v_add_f32_e32 v10, v10, v11
	s_waitcnt lgkmcnt(2)
	v_add_f32_e32 v10, v10, v12
	v_add_f32_e32 v10, v10, v13
	s_waitcnt lgkmcnt(1)
	v_add_f32_e32 v10, v10, v14
	v_add_f32_e32 v10, v10, v15
	v_mad_u64_u32 v[8:9], s[12:13], v9, s21, v[8:9]
	s_waitcnt lgkmcnt(0)
	v_add_f32_e32 v10, v10, v24
	v_ashrrev_i32_e32 v9, 31, v8
	v_add_f32_e32 v10, v10, v25
	v_lshl_add_u64 v[8:9], v[8:9], 2, s[66:67]
	s_waitcnt vmcnt(0)
	v_add_f32_e32 v10, v10, v23
	global_store_dword v[8:9], v10, off
	s_branch .LBB0_15
